# P6 epilogue: lane-permuted stores software-pipelined (bpermutes of the next group before the wait+store of the previous), on top of v57
# baseline (speedup 1.0000x reference)
.LBB0_731:
	ds_read_b128 v[148:151], v156
	ds_read_b128 v[160:163], v156 offset:1024
	ds_read_b128 v[164:167], v156 offset:2048
	ds_read_b128 v[168:171], v156 offset:3072
	ds_read_b128 v[176:179], v157
	ds_read_b128 v[180:183], v157 offset:1024
	ds_read_b128 v[184:187], v157 offset:2048
	ds_read_b128 v[188:191], v157 offset:3072
	s_add_u32 s22, s0, 0xfff00080
	s_addc_u32 s23, s1, -1
	s_cmp_eq_u32 s61, 60
	s_cselect_b32 s25, s5, s23
	s_cselect_b32 s24, s57, s22
	s_cselect_b32 s23, s21, s60
	s_cselect_b32 s22, s58, s59
	v_lshl_add_u64 v[152:153], s[0:1], 0, v[140:141]
	s_add_i32 m0, s34, 0xc000
	ds_read_b128 v[192:195], v158
	ds_read_b128 v[196:199], v158 offset:1024
	ds_read_b128 v[200:203], v158 offset:2048
	ds_read_b128 v[204:207], v158 offset:3072
	ds_read_b128 v[208:211], v158 offset:4096
	ds_read_b128 v[212:215], v158 offset:5120
	ds_read_b128 v[216:219], v158 offset:6144
	ds_read_b128 v[220:223], v158 offset:7168
	global_load_lds_dwordx4 v[152:153], off
	v_lshl_add_u64 v[152:153], s[0:1], 0, v[142:143]
	s_add_i32 m0, s34, 0xe000
	s_nop 0
	global_load_lds_dwordx4 v[152:153], off
	s_waitcnt vmcnt(8)
	s_waitcnt lgkmcnt(0)
	s_barrier
	s_setprio 1
	s_waitcnt lgkmcnt(0)
	v_mfma_f32_16x16x32_bf16 v[126:129], v[148:151], v[192:195], v[126:129]
	v_mfma_f32_16x16x32_bf16 v[122:125], v[164:167], v[192:195], v[122:125]
	v_mfma_f32_16x16x32_bf16 v[110:113], v[148:151], v[200:203], v[110:113]
	v_mfma_f32_16x16x32_bf16 v[106:109], v[164:167], v[200:203], v[106:109]
	v_mfma_f32_16x16x32_bf16 v[94:97], v[148:151], v[208:211], v[94:97]
	v_mfma_f32_16x16x32_bf16 v[90:93], v[164:167], v[208:211], v[90:93]
	v_mfma_f32_16x16x32_bf16 v[78:81], v[148:151], v[216:219], v[78:81]
	v_mfma_f32_16x16x32_bf16 v[74:77], v[164:167], v[216:219], v[74:77]
	v_mfma_f32_16x16x32_bf16 v[126:129], v[160:163], v[196:199], v[126:129]
	v_mfma_f32_16x16x32_bf16 v[122:125], v[168:171], v[196:199], v[122:125]
	v_mfma_f32_16x16x32_bf16 v[110:113], v[160:163], v[204:207], v[110:113]
	v_mfma_f32_16x16x32_bf16 v[106:109], v[168:171], v[204:207], v[106:109]
	v_mfma_f32_16x16x32_bf16 v[94:97], v[160:163], v[212:215], v[94:97]
	v_mfma_f32_16x16x32_bf16 v[90:93], v[168:171], v[212:215], v[90:93]
	v_mfma_f32_16x16x32_bf16 v[78:81], v[160:163], v[220:223], v[78:81]
	v_mfma_f32_16x16x32_bf16 v[74:77], v[168:171], v[220:223], v[74:77]
	s_setprio 0
	s_setprio 1
	v_mfma_f32_16x16x32_bf16 v[118:121], v[176:179], v[192:195], v[118:121]
	v_mfma_f32_16x16x32_bf16 v[114:117], v[184:187], v[192:195], v[114:117]
	v_mfma_f32_16x16x32_bf16 v[102:105], v[176:179], v[200:203], v[102:105]
	v_mfma_f32_16x16x32_bf16 v[98:101], v[184:187], v[200:203], v[98:101]
	v_mfma_f32_16x16x32_bf16 v[86:89], v[176:179], v[208:211], v[86:89]
	v_mfma_f32_16x16x32_bf16 v[82:85], v[184:187], v[208:211], v[82:85]
	v_mfma_f32_16x16x32_bf16 v[70:73], v[176:179], v[216:219], v[70:73]
	v_mfma_f32_16x16x32_bf16 v[66:69], v[184:187], v[216:219], v[66:69]
	v_mfma_f32_16x16x32_bf16 v[118:121], v[180:183], v[196:199], v[118:121]
	v_mfma_f32_16x16x32_bf16 v[114:117], v[188:191], v[196:199], v[114:117]
	v_mfma_f32_16x16x32_bf16 v[102:105], v[180:183], v[204:207], v[102:105]
	v_mfma_f32_16x16x32_bf16 v[98:101], v[188:191], v[204:207], v[98:101]
	v_mfma_f32_16x16x32_bf16 v[86:89], v[180:183], v[212:215], v[86:89]
	v_mfma_f32_16x16x32_bf16 v[82:85], v[188:191], v[212:215], v[82:85]
	v_mfma_f32_16x16x32_bf16 v[70:73], v[180:183], v[220:223], v[70:73]
	v_mfma_f32_16x16x32_bf16 v[66:69], v[188:191], v[220:223], v[66:69]
	s_setprio 0
	s_barrier
	s_add_i32 s62, s44, s31
	v_lshl_add_u64 v[152:153], s[22:23], 0, v[136:137]
	s_mov_b32 m0, s62
	ds_read_b128 v[192:195], v158 offset:16384
	ds_read_b128 v[196:199], v158 offset:17408
	ds_read_b128 v[200:203], v158 offset:18432
	ds_read_b128 v[204:207], v158 offset:19456
	ds_read_b128 v[208:211], v158 offset:20480
	ds_read_b128 v[212:215], v158 offset:21504
	ds_read_b128 v[216:219], v158 offset:22528
	ds_read_b128 v[220:223], v158 offset:23552
	global_load_lds_dwordx4 v[152:153], off
	s_add_i32 m0, s62, 0x2000
	s_add_u32 s62, s22, 0x100000
	v_lshl_add_u64 v[172:173], s[22:23], 0, v[130:131]
	s_addc_u32 s63, s23, 0
	s_add_i32 s64, s45, s31
	global_load_lds_dwordx4 v[172:173], off
	v_lshl_add_u64 v[224:225], s[62:63], 0, v[136:137]
	s_mov_b32 m0, s64
	v_lshl_add_u64 v[226:227], s[24:25], 0, v[132:133]
	global_load_lds_dwordx4 v[224:225], off
	v_lshl_add_u64 v[224:225], s[62:63], 0, v[130:131]
	s_add_i32 m0, s64, 0x2000
	s_nop 0
	global_load_lds_dwordx4 v[224:225], off
	v_lshl_add_u64 v[224:225], s[24:25], 0, v[138:139]
	s_mov_b32 m0, s34
	s_nop 0
	global_load_lds_dwordx4 v[224:225], off
	s_mov_b32 m0, s35
	s_nop 0
	global_load_lds_dwordx4 v[226:227], off
	s_waitcnt vmcnt(8)
	s_waitcnt lgkmcnt(0)
	s_barrier
	s_setprio 1
	s_waitcnt lgkmcnt(0)
	v_mfma_f32_16x16x32_bf16 v[62:65], v[148:151], v[192:195], v[62:65]
	v_mfma_f32_16x16x32_bf16 v[58:61], v[164:167], v[192:195], v[58:61]
	v_mfma_f32_16x16x32_bf16 v[46:49], v[148:151], v[200:203], v[46:49]
	v_mfma_f32_16x16x32_bf16 v[42:45], v[164:167], v[200:203], v[42:45]
	v_mfma_f32_16x16x32_bf16 v[30:33], v[148:151], v[208:211], v[30:33]
	v_mfma_f32_16x16x32_bf16 v[26:29], v[164:167], v[208:211], v[26:29]
	v_mfma_f32_16x16x32_bf16 v[14:17], v[148:151], v[216:219], v[14:17]
	v_mfma_f32_16x16x32_bf16 v[10:13], v[164:167], v[216:219], v[10:13]
	v_mfma_f32_16x16x32_bf16 v[62:65], v[160:163], v[196:199], v[62:65]
	v_mfma_f32_16x16x32_bf16 v[58:61], v[168:171], v[196:199], v[58:61]
	v_mfma_f32_16x16x32_bf16 v[46:49], v[160:163], v[204:207], v[46:49]
	v_mfma_f32_16x16x32_bf16 v[42:45], v[168:171], v[204:207], v[42:45]
	v_mfma_f32_16x16x32_bf16 v[30:33], v[160:163], v[212:215], v[30:33]
	v_mfma_f32_16x16x32_bf16 v[26:29], v[168:171], v[212:215], v[26:29]
	v_mfma_f32_16x16x32_bf16 v[14:17], v[160:163], v[220:223], v[14:17]
	v_mfma_f32_16x16x32_bf16 v[10:13], v[168:171], v[220:223], v[10:13]
	s_setprio 0
	s_setprio 1
	v_mfma_f32_16x16x32_bf16 v[54:57], v[176:179], v[192:195], v[54:57]
	v_mfma_f32_16x16x32_bf16 v[50:53], v[184:187], v[192:195], v[50:53]
	v_mfma_f32_16x16x32_bf16 v[38:41], v[176:179], v[200:203], v[38:41]
	v_mfma_f32_16x16x32_bf16 v[34:37], v[184:187], v[200:203], v[34:37]
	v_mfma_f32_16x16x32_bf16 v[22:25], v[176:179], v[208:211], v[22:25]
	v_mfma_f32_16x16x32_bf16 v[18:21], v[184:187], v[208:211], v[18:21]
	v_mfma_f32_16x16x32_bf16 v[6:9], v[176:179], v[216:219], v[6:9]
	v_mfma_f32_16x16x32_bf16 v[2:5], v[184:187], v[216:219], v[2:5]
	v_mfma_f32_16x16x32_bf16 v[54:57], v[180:183], v[196:199], v[54:57]
	v_mfma_f32_16x16x32_bf16 v[50:53], v[188:191], v[196:199], v[50:53]
	v_mfma_f32_16x16x32_bf16 v[38:41], v[180:183], v[204:207], v[38:41]
	v_mfma_f32_16x16x32_bf16 v[34:37], v[188:191], v[204:207], v[34:37]
	v_mfma_f32_16x16x32_bf16 v[22:25], v[180:183], v[212:215], v[22:25]
	v_mfma_f32_16x16x32_bf16 v[18:21], v[188:191], v[212:215], v[18:21]
	v_mfma_f32_16x16x32_bf16 v[6:9], v[180:183], v[220:223], v[6:9]
	v_mfma_f32_16x16x32_bf16 v[2:5], v[188:191], v[220:223], v[2:5]
	s_setprio 0
	s_barrier
	s_add_i32 s62, 0, 0x18000
	v_add_u32_e32 v159, s62, v135
	s_add_i32 s63, 0, 0x1c000
	ds_read_b128 v[148:151], v159
	ds_read_b128 v[160:163], v159 offset:1024
	ds_read_b128 v[164:167], v159 offset:2048
	ds_read_b128 v[168:171], v159 offset:3072
	v_add_u32_e32 v159, s63, v135
	ds_read_b128 v[176:179], v159
	ds_read_b128 v[180:183], v159 offset:1024
	ds_read_b128 v[184:187], v159 offset:2048
	ds_read_b128 v[188:191], v159 offset:3072
	s_add_u32 s24, s24, 0x100000
	s_addc_u32 s25, s25, 0
	s_mov_b32 m0, s36
	v_lshl_add_u64 v[228:229], s[24:25], 0, v[138:139]
	ds_read_b128 v[192:195], v158 offset:32768
	ds_read_b128 v[196:199], v158 offset:33792
	ds_read_b128 v[200:203], v158 offset:34816
	ds_read_b128 v[204:207], v158 offset:35840
	ds_read_b128 v[208:211], v158 offset:36864
	ds_read_b128 v[212:215], v158 offset:37888
	ds_read_b128 v[216:219], v158 offset:38912
	ds_read_b128 v[220:223], v158 offset:39936
	global_load_lds_dwordx4 v[228:229], off
	v_lshl_add_u64 v[228:229], s[24:25], 0, v[132:133]
	s_mov_b32 m0, s37
	s_nop 0
	global_load_lds_dwordx4 v[228:229], off
	s_waitcnt vmcnt(8)
	s_waitcnt lgkmcnt(0)
	s_barrier
	s_setprio 1
	s_waitcnt lgkmcnt(0)
	v_mfma_f32_16x16x32_bf16 v[126:129], v[148:151], v[192:195], v[126:129]
	v_mfma_f32_16x16x32_bf16 v[122:125], v[164:167], v[192:195], v[122:125]
	v_mfma_f32_16x16x32_bf16 v[110:113], v[148:151], v[200:203], v[110:113]
	v_mfma_f32_16x16x32_bf16 v[106:109], v[164:167], v[200:203], v[106:109]
	v_mfma_f32_16x16x32_bf16 v[94:97], v[148:151], v[208:211], v[94:97]
	v_mfma_f32_16x16x32_bf16 v[90:93], v[164:167], v[208:211], v[90:93]
	v_mfma_f32_16x16x32_bf16 v[78:81], v[148:151], v[216:219], v[78:81]
	v_mfma_f32_16x16x32_bf16 v[74:77], v[164:167], v[216:219], v[74:77]
	v_mfma_f32_16x16x32_bf16 v[126:129], v[160:163], v[196:199], v[126:129]
	v_mfma_f32_16x16x32_bf16 v[122:125], v[168:171], v[196:199], v[122:125]
	v_mfma_f32_16x16x32_bf16 v[110:113], v[160:163], v[204:207], v[110:113]
	v_mfma_f32_16x16x32_bf16 v[106:109], v[168:171], v[204:207], v[106:109]
	v_mfma_f32_16x16x32_bf16 v[94:97], v[160:163], v[212:215], v[94:97]
	v_mfma_f32_16x16x32_bf16 v[90:93], v[168:171], v[212:215], v[90:93]
	v_mfma_f32_16x16x32_bf16 v[78:81], v[160:163], v[220:223], v[78:81]
	v_mfma_f32_16x16x32_bf16 v[74:77], v[168:171], v[220:223], v[74:77]
	s_setprio 0
	s_setprio 1
	v_mfma_f32_16x16x32_bf16 v[118:121], v[176:179], v[192:195], v[118:121]
	v_mfma_f32_16x16x32_bf16 v[114:117], v[184:187], v[192:195], v[114:117]
	v_mfma_f32_16x16x32_bf16 v[102:105], v[176:179], v[200:203], v[102:105]
	v_mfma_f32_16x16x32_bf16 v[98:101], v[184:187], v[200:203], v[98:101]
	v_mfma_f32_16x16x32_bf16 v[86:89], v[176:179], v[208:211], v[86:89]
	v_mfma_f32_16x16x32_bf16 v[82:85], v[184:187], v[208:211], v[82:85]
	v_mfma_f32_16x16x32_bf16 v[70:73], v[176:179], v[216:219], v[70:73]
	v_mfma_f32_16x16x32_bf16 v[66:69], v[184:187], v[216:219], v[66:69]
	v_mfma_f32_16x16x32_bf16 v[118:121], v[180:183], v[196:199], v[118:121]
	v_mfma_f32_16x16x32_bf16 v[114:117], v[188:191], v[196:199], v[114:117]
	v_mfma_f32_16x16x32_bf16 v[102:105], v[180:183], v[204:207], v[102:105]
	v_mfma_f32_16x16x32_bf16 v[98:101], v[188:191], v[204:207], v[98:101]
	v_mfma_f32_16x16x32_bf16 v[86:89], v[180:183], v[212:215], v[86:89]
	v_mfma_f32_16x16x32_bf16 v[82:85], v[188:191], v[212:215], v[82:85]
	v_mfma_f32_16x16x32_bf16 v[70:73], v[180:183], v[220:223], v[70:73]
	v_mfma_f32_16x16x32_bf16 v[66:69], v[188:191], v[220:223], v[66:69]
	s_setprio 0
	s_barrier
	s_add_i32 s24, s62, s31
	v_lshl_add_u64 v[152:153], v[152:153], 0, s[16:17]
	s_mov_b32 m0, s24
	ds_read_b128 v[192:195], v158 offset:49152
	ds_read_b128 v[196:199], v158 offset:50176
	ds_read_b128 v[200:203], v158 offset:51200
	ds_read_b128 v[204:207], v158 offset:52224
	ds_read_b128 v[208:211], v158 offset:53248
	ds_read_b128 v[212:215], v158 offset:54272
	ds_read_b128 v[216:219], v158 offset:55296
	ds_read_b128 v[220:223], v158 offset:56320
	global_load_lds_dwordx4 v[152:153], off
	s_add_i32 m0, s24, 0x2000
	s_add_u32 s22, s22, 0x100080
	v_lshl_add_u64 v[152:153], v[172:173], 0, s[16:17]
	s_addc_u32 s23, s23, 0
	s_add_i32 s24, s63, s31
	global_load_lds_dwordx4 v[152:153], off
	v_lshl_add_u64 v[152:153], s[22:23], 0, v[136:137]
	s_mov_b32 m0, s24
	s_nop 0
	global_load_lds_dwordx4 v[152:153], off
	v_lshl_add_u64 v[152:153], s[22:23], 0, v[130:131]
	s_add_i32 m0, s24, 0x2000
	s_nop 0
	global_load_lds_dwordx4 v[152:153], off
	v_lshl_add_u64 v[152:153], v[224:225], 0, s[16:17]
	s_mov_b32 m0, s40
	s_nop 0
	global_load_lds_dwordx4 v[152:153], off
	v_lshl_add_u64 v[152:153], v[226:227], 0, s[16:17]
	s_mov_b32 m0, s41
	s_nop 0
	global_load_lds_dwordx4 v[152:153], off
	s_waitcnt vmcnt(8)
	s_waitcnt lgkmcnt(0)
	s_barrier
	s_setprio 1
	s_waitcnt lgkmcnt(0)
	v_mfma_f32_16x16x32_bf16 v[62:65], v[148:151], v[192:195], v[62:65]
	v_mfma_f32_16x16x32_bf16 v[58:61], v[164:167], v[192:195], v[58:61]
	v_mfma_f32_16x16x32_bf16 v[46:49], v[148:151], v[200:203], v[46:49]
	v_mfma_f32_16x16x32_bf16 v[42:45], v[164:167], v[200:203], v[42:45]
	v_mfma_f32_16x16x32_bf16 v[30:33], v[148:151], v[208:211], v[30:33]
	v_mfma_f32_16x16x32_bf16 v[26:29], v[164:167], v[208:211], v[26:29]
	v_mfma_f32_16x16x32_bf16 v[14:17], v[148:151], v[216:219], v[14:17]
	v_mfma_f32_16x16x32_bf16 v[10:13], v[164:167], v[216:219], v[10:13]
	v_mfma_f32_16x16x32_bf16 v[62:65], v[160:163], v[196:199], v[62:65]
	v_mfma_f32_16x16x32_bf16 v[58:61], v[168:171], v[196:199], v[58:61]
	v_mfma_f32_16x16x32_bf16 v[46:49], v[160:163], v[204:207], v[46:49]
	v_mfma_f32_16x16x32_bf16 v[42:45], v[168:171], v[204:207], v[42:45]
	v_mfma_f32_16x16x32_bf16 v[30:33], v[160:163], v[212:215], v[30:33]
	v_mfma_f32_16x16x32_bf16 v[26:29], v[168:171], v[212:215], v[26:29]
	v_mfma_f32_16x16x32_bf16 v[14:17], v[160:163], v[220:223], v[14:17]
	v_mfma_f32_16x16x32_bf16 v[10:13], v[168:171], v[220:223], v[10:13]
	s_setprio 0
	s_setprio 1
	v_mfma_f32_16x16x32_bf16 v[54:57], v[176:179], v[192:195], v[54:57]
	v_mfma_f32_16x16x32_bf16 v[50:53], v[184:187], v[192:195], v[50:53]
	v_mfma_f32_16x16x32_bf16 v[38:41], v[176:179], v[200:203], v[38:41]
	v_mfma_f32_16x16x32_bf16 v[34:37], v[184:187], v[200:203], v[34:37]
	v_mfma_f32_16x16x32_bf16 v[22:25], v[176:179], v[208:211], v[22:25]
	v_mfma_f32_16x16x32_bf16 v[18:21], v[184:187], v[208:211], v[18:21]
	v_mfma_f32_16x16x32_bf16 v[6:9], v[176:179], v[216:219], v[6:9]
	v_mfma_f32_16x16x32_bf16 v[2:5], v[184:187], v[216:219], v[2:5]
	v_mfma_f32_16x16x32_bf16 v[54:57], v[180:183], v[196:199], v[54:57]
	v_mfma_f32_16x16x32_bf16 v[50:53], v[188:191], v[196:199], v[50:53]
	v_mfma_f32_16x16x32_bf16 v[38:41], v[180:183], v[204:207], v[38:41]
	v_mfma_f32_16x16x32_bf16 v[34:37], v[188:191], v[204:207], v[34:37]
	v_mfma_f32_16x16x32_bf16 v[22:25], v[180:183], v[212:215], v[22:25]
	v_mfma_f32_16x16x32_bf16 v[18:21], v[188:191], v[212:215], v[18:21]
	v_mfma_f32_16x16x32_bf16 v[6:9], v[180:183], v[220:223], v[6:9]
	v_mfma_f32_16x16x32_bf16 v[2:5], v[188:191], v[220:223], v[2:5]
	s_setprio 0
	s_barrier
	s_add_i32 s61, s61, 2
	s_add_u32 s0, s0, 0x100
	s_addc_u32 s1, s1, 0
	s_add_u32 s59, s59, 0x100
	s_addc_u32 s60, s60, 0
	s_cmp_gt_u32 s61, 61
	s_cbranch_scc0 .LBB0_731
	v_and_b32_e32 v165, 3, v174
	v_lshrrev_b32_e32 v170, 2, v174
	v_lshlrev_b32_e32 v164, 6, v165
	v_and_or_b32 v164, v174, 60, v164
	v_and_b32_e32 v171, 15, v174
	v_sub_u32_e32 v170, v170, v171
	v_lshrrev_b32_e32 v171, 4, v174
	v_sub_u32_e32 v165, v165, v171
	v_mul_i32_i24_e32 v170, 0xac00, v170
	v_lshl_add_u32 v166, v165, 4, v170
	v_ashrrev_i32_e32 v167, 31, v166
	s_lshl_b32 s5, s56, 8
	s_add_i32 s5, s5, s39
	v_or_b32_e32 v159, s5, v1
	v_cmp_lt_i32_e64 s[0:1], s46, v159
	s_and_b64 s[22:23], s[0:1], s[18:19]
	v_mov_b64_e32 v[150:151], 0
	s_and_saveexec_b64 s[0:1], s[22:23]
	v_add_u32_e32 v148, 0xffffe000, v159
	v_lshrrev_b32_e32 v148, 2, v148
	v_and_b32_e32 v148, 0x3ffffff2, v148
	v_add_u32_e32 v150, v148, v154
	v_mov_b64_e32 v[148:149], s[10:11]
	v_mad_u64_u32 v[150:151], s[22:23], v150, s47, v[148:149]
	s_or_b64 exec, exec, s[0:1]
	v_lshl_or_b32 v148, s55, 8, v155
	v_mov_b64_e32 v[152:153], s[6:7]
	v_ashrrev_i32_e32 v149, 31, v148
	v_mad_i64_i32 v[152:153], s[0:1], v159, s48, v[152:153]
	v_lshl_add_u64 v[152:153], v[148:149], 1, v[152:153]
	v_cmp_ne_u64_e64 s[0:1], 0, v[150:151]
	v_lshl_add_u64 v[150:151], v[148:149], 2, v[150:151]
	v_cvt_pk_bf16_f32 v160, v126, v127
	v_cvt_pk_bf16_f32 v161, v128, v129
	v_cvt_pk_bf16_f32 v162, v122, v123
	v_cvt_pk_bf16_f32 v163, v124, v125
	ds_bpermute_b32 v160, v164, v160
	ds_bpermute_b32 v161, v164, v161
	ds_bpermute_b32 v162, v164, v162
	ds_bpermute_b32 v163, v164, v163
	v_lshl_add_u64 v[168:169], v[166:167], 0, v[152:153]
	s_and_saveexec_b64 s[22:23], s[0:1]
	s_cbranch_execz .LBB0_736
	global_store_dwordx4 v[150:151], v[126:129], off
	global_store_dwordx4 v[150:151], v[122:125], off offset:16
.LBB0_736:
	s_or_b64 exec, exec, s[22:23]
	s_nop 0
	v_cvt_pk_bf16_f32 v122, v118, v119
	v_cvt_pk_bf16_f32 v123, v120, v121
	v_cvt_pk_bf16_f32 v124, v114, v115
	v_cvt_pk_bf16_f32 v125, v116, v117
	ds_bpermute_b32 v122, v164, v122
	ds_bpermute_b32 v123, v164, v123
	ds_bpermute_b32 v124, v164, v124
	ds_bpermute_b32 v125, v164, v125
	v_lshl_add_u64 v[170:171], v[166:167], 0, v[152:153]
	s_waitcnt lgkmcnt(4)
	global_store_dwordx4 v[168:169], v[160:163], off
	s_and_saveexec_b64 s[22:23], s[0:1]
	s_cbranch_execz .LBB0_738
	global_store_dwordx4 v[150:151], v[118:121], off offset:512
	global_store_dwordx4 v[150:151], v[114:117], off offset:528
.LBB0_738:
	s_or_b64 exec, exec, s[22:23]
	s_nop 0
	v_or_b32_e32 v116, 16, v159
	v_cmp_lt_i32_e64 s[0:1], s46, v116
	s_and_b64 s[22:23], s[0:1], s[18:19]
	v_mov_b64_e32 v[114:115], 0
	s_and_saveexec_b64 s[0:1], s[22:23]
	v_add_u32_e32 v114, 0xffffe010, v159
	v_lshrrev_b32_e32 v114, 2, v114
	v_and_b32_e32 v114, 0x3ffffff6, v114
	v_add_u32_e32 v117, v114, v154
	v_mov_b64_e32 v[114:115], s[10:11]
	v_mad_u64_u32 v[114:115], s[22:23], v117, s47, v[114:115]
	s_or_b64 exec, exec, s[0:1]
	v_mov_b64_e32 v[118:119], s[6:7]
	v_mad_i64_i32 v[116:117], s[0:1], v116, s48, v[118:119]
	v_lshl_add_u64 v[116:117], v[148:149], 1, v[116:117]
	v_cmp_ne_u64_e64 s[0:1], 0, v[114:115]
	v_lshl_add_u64 v[114:115], v[148:149], 2, v[114:115]
	v_cvt_pk_bf16_f32 v118, v110, v111
	v_cvt_pk_bf16_f32 v119, v112, v113
	v_cvt_pk_bf16_f32 v120, v106, v107
	v_cvt_pk_bf16_f32 v121, v108, v109
	ds_bpermute_b32 v118, v164, v118
	ds_bpermute_b32 v119, v164, v119
	ds_bpermute_b32 v120, v164, v120
	ds_bpermute_b32 v121, v164, v121
	v_lshl_add_u64 v[168:169], v[166:167], 0, v[116:117]
	s_waitcnt lgkmcnt(4)
	global_store_dwordx4 v[170:171], v[122:125], off offset:256
	s_and_saveexec_b64 s[22:23], s[0:1]
	s_cbranch_execz .LBB0_742
	global_store_dwordx4 v[114:115], v[110:113], off
	global_store_dwordx4 v[114:115], v[106:109], off offset:16
.LBB0_742:
	s_or_b64 exec, exec, s[22:23]
	s_nop 0
	v_cvt_pk_bf16_f32 v106, v102, v103
	v_cvt_pk_bf16_f32 v107, v104, v105
	v_cvt_pk_bf16_f32 v108, v98, v99
	v_cvt_pk_bf16_f32 v109, v100, v101
	ds_bpermute_b32 v106, v164, v106
	ds_bpermute_b32 v107, v164, v107
	ds_bpermute_b32 v108, v164, v108
	ds_bpermute_b32 v109, v164, v109
	v_lshl_add_u64 v[170:171], v[166:167], 0, v[116:117]
	s_waitcnt lgkmcnt(4)
	global_store_dwordx4 v[168:169], v[118:121], off
	s_and_saveexec_b64 s[22:23], s[0:1]
	s_cbranch_execz .LBB0_744
	global_store_dwordx4 v[114:115], v[102:105], off offset:512
	global_store_dwordx4 v[114:115], v[98:101], off offset:528
.LBB0_744:
	s_or_b64 exec, exec, s[22:23]
	s_nop 0
	v_or_b32_e32 v100, 32, v159
	v_cmp_lt_i32_e64 s[0:1], s46, v100
	s_and_b64 s[22:23], s[0:1], s[18:19]
	v_mov_b64_e32 v[98:99], 0
	s_and_saveexec_b64 s[0:1], s[22:23]
	v_add_u32_e32 v98, 0xffffe020, v159
	v_lshrrev_b32_e32 v98, 2, v98
	v_and_b32_e32 v98, 0x3ffffffa, v98
	v_add_u32_e32 v101, v98, v154
	v_mov_b64_e32 v[98:99], s[10:11]
	v_mad_u64_u32 v[98:99], s[22:23], v101, s47, v[98:99]
	s_or_b64 exec, exec, s[0:1]
	v_mov_b64_e32 v[102:103], s[6:7]
	v_mad_i64_i32 v[100:101], s[0:1], v100, s48, v[102:103]
	v_lshl_add_u64 v[100:101], v[148:149], 1, v[100:101]
	v_cmp_ne_u64_e64 s[0:1], 0, v[98:99]
	v_lshl_add_u64 v[98:99], v[148:149], 2, v[98:99]
	v_cvt_pk_bf16_f32 v102, v94, v95
	v_cvt_pk_bf16_f32 v103, v96, v97
	v_cvt_pk_bf16_f32 v104, v90, v91
	v_cvt_pk_bf16_f32 v105, v92, v93
	ds_bpermute_b32 v102, v164, v102
	ds_bpermute_b32 v103, v164, v103
	ds_bpermute_b32 v104, v164, v104
	ds_bpermute_b32 v105, v164, v105
	v_lshl_add_u64 v[168:169], v[166:167], 0, v[100:101]
	s_waitcnt lgkmcnt(4)
	global_store_dwordx4 v[170:171], v[106:109], off offset:256
	s_and_saveexec_b64 s[22:23], s[0:1]
	s_cbranch_execz .LBB0_748
	global_store_dwordx4 v[98:99], v[94:97], off
	global_store_dwordx4 v[98:99], v[90:93], off offset:16
.LBB0_748:
	s_or_b64 exec, exec, s[22:23]
	s_nop 0
	v_cvt_pk_bf16_f32 v90, v86, v87
	v_cvt_pk_bf16_f32 v91, v88, v89
	v_cvt_pk_bf16_f32 v92, v82, v83
	v_cvt_pk_bf16_f32 v93, v84, v85
	ds_bpermute_b32 v90, v164, v90
	ds_bpermute_b32 v91, v164, v91
	ds_bpermute_b32 v92, v164, v92
	ds_bpermute_b32 v93, v164, v93
	v_lshl_add_u64 v[170:171], v[166:167], 0, v[100:101]
	s_waitcnt lgkmcnt(4)
	global_store_dwordx4 v[168:169], v[102:105], off
	s_and_saveexec_b64 s[22:23], s[0:1]
	s_cbranch_execz .LBB0_750
	global_store_dwordx4 v[98:99], v[86:89], off offset:512
	global_store_dwordx4 v[98:99], v[82:85], off offset:528

.LBB0_758:
	s_or_b64 exec, exec, s[22:23]
	v_mov_b64_e32 v[86:87], s[6:7]
	v_mad_i64_i32 v[84:85], s[0:1], v84, s48, v[86:87]
	v_lshl_add_u64 v[84:85], v[148:149], 1, v[84:85]
	v_cmp_ne_u64_e64 s[0:1], 0, v[82:83]
	v_lshl_add_u64 v[82:83], v[148:149], 2, v[82:83]
	v_cvt_pk_bf16_f32 v86, v78, v79
	v_cvt_pk_bf16_f32 v87, v80, v81
	v_cvt_pk_bf16_f32 v88, v74, v75
	v_cvt_pk_bf16_f32 v89, v76, v77
	ds_bpermute_b32 v86, v164, v86
	ds_bpermute_b32 v87, v164, v87
	ds_bpermute_b32 v88, v164, v88
	ds_bpermute_b32 v89, v164, v89
	v_lshl_add_u64 v[168:169], v[166:167], 0, v[84:85]
	s_waitcnt lgkmcnt(4)
	global_store_dwordx4 v[170:171], v[90:93], off offset:256
	s_and_saveexec_b64 s[22:23], s[0:1]
	s_cbranch_execz .LBB0_760
	global_store_dwordx4 v[82:83], v[78:81], off
	global_store_dwordx4 v[82:83], v[74:77], off offset:16
.LBB0_760:
	s_or_b64 exec, exec, s[22:23]
	s_nop 0
	v_cvt_pk_bf16_f32 v74, v70, v71
	v_cvt_pk_bf16_f32 v75, v72, v73
	v_cvt_pk_bf16_f32 v76, v66, v67
	v_cvt_pk_bf16_f32 v77, v68, v69
	ds_bpermute_b32 v74, v164, v74
	ds_bpermute_b32 v75, v164, v75
	ds_bpermute_b32 v76, v164, v76
	ds_bpermute_b32 v77, v164, v77
	v_lshl_add_u64 v[170:171], v[166:167], 0, v[84:85]
	s_waitcnt lgkmcnt(4)
	global_store_dwordx4 v[168:169], v[86:89], off
	s_waitcnt lgkmcnt(0)
	global_store_dwordx4 v[170:171], v[74:77], off offset:256
	s_and_saveexec_b64 s[22:23], s[0:1]
	s_cbranch_execz .LBB0_762
	global_store_dwordx4 v[82:83], v[70:73], off offset:512
	global_store_dwordx4 v[82:83], v[66:69], off offset:528
.LBB0_762:
	s_or_b64 exec, exec, s[22:23]
	v_cmp_lt_i32_e64 s[0:1], s51, v159
	s_and_b64 s[22:23], s[0:1], s[18:19]
	v_mov_b64_e32 v[66:67], 0
	s_and_saveexec_b64 s[0:1], s[22:23]
	v_add_u32_e32 v66, 0xffffe080, v159
	v_lshrrev_b32_e32 v66, 2, v66
	v_and_b32_e32 v66, 0x3ffffff2, v66
	v_add_u32_e32 v68, v66, v154
	v_mov_b64_e32 v[66:67], s[10:11]
	v_mad_u64_u32 v[66:67], s[22:23], v68, s47, v[66:67]
	s_or_b64 exec, exec, s[0:1]
	v_add_u32_e32 v70, 0x80, v159
	v_mov_b64_e32 v[68:69], s[6:7]
	v_mad_i64_i32 v[68:69], s[0:1], v70, s48, v[68:69]
	v_lshl_add_u64 v[68:69], v[148:149], 1, v[68:69]
	v_cmp_ne_u64_e64 s[0:1], 0, v[66:67]
	v_lshl_add_u64 v[66:67], v[148:149], 2, v[66:67]
	v_cvt_pk_bf16_f32 v72, v62, v63
	v_cvt_pk_bf16_f32 v73, v64, v65
	v_cvt_pk_bf16_f32 v74, v58, v59
	v_cvt_pk_bf16_f32 v75, v60, v61
	ds_bpermute_b32 v72, v164, v72
	ds_bpermute_b32 v73, v164, v73
	ds_bpermute_b32 v74, v164, v74
	ds_bpermute_b32 v75, v164, v75
	v_lshl_add_u64 v[168:169], v[166:167], 0, v[68:69]
	s_and_saveexec_b64 s[22:23], s[0:1]
	s_cbranch_execz .LBB0_766
	global_store_dwordx4 v[66:67], v[62:65], off
	global_store_dwordx4 v[66:67], v[58:61], off offset:16
.LBB0_766:
	s_or_b64 exec, exec, s[22:23]
	s_nop 0
	v_cvt_pk_bf16_f32 v58, v54, v55
	v_cvt_pk_bf16_f32 v59, v56, v57
	v_cvt_pk_bf16_f32 v60, v50, v51
	v_cvt_pk_bf16_f32 v61, v52, v53
	ds_bpermute_b32 v58, v164, v58
	ds_bpermute_b32 v59, v164, v59
	ds_bpermute_b32 v60, v164, v60
	ds_bpermute_b32 v61, v164, v61
	v_lshl_add_u64 v[170:171], v[166:167], 0, v[68:69]
	s_waitcnt lgkmcnt(4)
	global_store_dwordx4 v[168:169], v[72:75], off
	s_and_saveexec_b64 s[22:23], s[0:1]
	s_cbranch_execz .LBB0_768
	global_store_dwordx4 v[66:67], v[54:57], off offset:512
	global_store_dwordx4 v[66:67], v[50:53], off offset:528
.LBB0_768:
	s_or_b64 exec, exec, s[22:23]
	v_cmp_lt_i32_e64 s[0:1], s52, v159
	s_and_b64 s[22:23], s[0:1], s[18:19]
	v_mov_b64_e32 v[50:51], 0
	s_and_saveexec_b64 s[0:1], s[22:23]
	v_add_u32_e32 v50, 0xffffe090, v159
	v_lshrrev_b32_e32 v50, 2, v50
	v_and_b32_e32 v50, 0x3ffffff6, v50
	v_add_u32_e32 v52, v50, v154
	v_mov_b64_e32 v[50:51], s[10:11]
	v_mad_u64_u32 v[50:51], s[22:23], v52, s47, v[50:51]
	s_or_b64 exec, exec, s[0:1]
	v_add_u32_e32 v54, 0x90, v159
	v_mov_b64_e32 v[52:53], s[6:7]
	v_mad_i64_i32 v[52:53], s[0:1], v54, s48, v[52:53]
	v_lshl_add_u64 v[52:53], v[148:149], 1, v[52:53]
	v_cmp_ne_u64_e64 s[0:1], 0, v[50:51]
	v_lshl_add_u64 v[50:51], v[148:149], 2, v[50:51]
	v_cvt_pk_bf16_f32 v54, v46, v47
	v_cvt_pk_bf16_f32 v55, v48, v49
	v_cvt_pk_bf16_f32 v56, v42, v43
	v_cvt_pk_bf16_f32 v57, v44, v45
	ds_bpermute_b32 v54, v164, v54
	ds_bpermute_b32 v55, v164, v55
	ds_bpermute_b32 v56, v164, v56
	ds_bpermute_b32 v57, v164, v57
	v_lshl_add_u64 v[168:169], v[166:167], 0, v[52:53]
	s_waitcnt lgkmcnt(4)
	global_store_dwordx4 v[170:171], v[58:61], off offset:256
	s_and_saveexec_b64 s[22:23], s[0:1]
	s_cbranch_execz .LBB0_772
	global_store_dwordx4 v[50:51], v[46:49], off
	global_store_dwordx4 v[50:51], v[42:45], off offset:16
.LBB0_772:
	s_or_b64 exec, exec, s[22:23]
	s_nop 0
	v_cvt_pk_bf16_f32 v42, v38, v39
	v_cvt_pk_bf16_f32 v43, v40, v41
	v_cvt_pk_bf16_f32 v44, v34, v35
	v_cvt_pk_bf16_f32 v45, v36, v37
	ds_bpermute_b32 v42, v164, v42
	ds_bpermute_b32 v43, v164, v43
	ds_bpermute_b32 v44, v164, v44
	ds_bpermute_b32 v45, v164, v45
	v_lshl_add_u64 v[170:171], v[166:167], 0, v[52:53]
	s_waitcnt lgkmcnt(4)
	global_store_dwordx4 v[168:169], v[54:57], off
	s_and_saveexec_b64 s[22:23], s[0:1]
	s_cbranch_execz .LBB0_774
	global_store_dwordx4 v[50:51], v[38:41], off offset:512
	global_store_dwordx4 v[50:51], v[34:37], off offset:528
.LBB0_774:
	s_or_b64 exec, exec, s[22:23]
	v_cmp_lt_i32_e64 s[0:1], s53, v159
	s_and_b64 s[22:23], s[0:1], s[18:19]
	v_mov_b64_e32 v[34:35], 0
	s_and_saveexec_b64 s[0:1], s[22:23]
	v_add_u32_e32 v34, 0xffffe0a0, v159
	v_lshrrev_b32_e32 v34, 2, v34
	v_and_b32_e32 v34, 0x3ffffffa, v34
	v_add_u32_e32 v36, v34, v154
	v_mov_b64_e32 v[34:35], s[10:11]
	v_mad_u64_u32 v[34:35], s[22:23], v36, s47, v[34:35]
	s_or_b64 exec, exec, s[0:1]
	v_add_u32_e32 v38, 0xa0, v159
	v_mov_b64_e32 v[36:37], s[6:7]
	v_mad_i64_i32 v[36:37], s[0:1], v38, s48, v[36:37]
	v_lshl_add_u64 v[36:37], v[148:149], 1, v[36:37]
	v_cmp_ne_u64_e64 s[0:1], 0, v[34:35]
	v_lshl_add_u64 v[34:35], v[148:149], 2, v[34:35]
	v_cvt_pk_bf16_f32 v38, v30, v31
	v_cvt_pk_bf16_f32 v39, v32, v33
	v_cvt_pk_bf16_f32 v40, v26, v27
	v_cvt_pk_bf16_f32 v41, v28, v29
	ds_bpermute_b32 v38, v164, v38
	ds_bpermute_b32 v39, v164, v39
	ds_bpermute_b32 v40, v164, v40
	ds_bpermute_b32 v41, v164, v41
	v_lshl_add_u64 v[168:169], v[166:167], 0, v[36:37]
	s_waitcnt lgkmcnt(4)
	global_store_dwordx4 v[170:171], v[42:45], off offset:256
	s_and_saveexec_b64 s[22:23], s[0:1]
	s_cbranch_execz .LBB0_778
	global_store_dwordx4 v[34:35], v[30:33], off
	global_store_dwordx4 v[34:35], v[26:29], off offset:16
.LBB0_778:
	s_or_b64 exec, exec, s[22:23]
	s_nop 0
	v_cvt_pk_bf16_f32 v26, v22, v23
	v_cvt_pk_bf16_f32 v27, v24, v25
	v_cvt_pk_bf16_f32 v28, v18, v19
	v_cvt_pk_bf16_f32 v29, v20, v21
	ds_bpermute_b32 v26, v164, v26
	ds_bpermute_b32 v27, v164, v27
	ds_bpermute_b32 v28, v164, v28
	ds_bpermute_b32 v29, v164, v29
	v_lshl_add_u64 v[170:171], v[166:167], 0, v[36:37]
	s_waitcnt lgkmcnt(4)
	global_store_dwordx4 v[168:169], v[38:41], off
	s_and_saveexec_b64 s[22:23], s[0:1]
	s_cbranch_execz .LBB0_780
	global_store_dwordx4 v[34:35], v[22:25], off offset:512
	global_store_dwordx4 v[34:35], v[18:21], off offset:528

.LBB0_788:
	s_or_b64 exec, exec, s[22:23]
	v_mov_b64_e32 v[22:23], s[6:7]
	v_mad_i64_i32 v[20:21], s[0:1], v20, s48, v[22:23]
	v_lshl_add_u64 v[20:21], v[148:149], 1, v[20:21]
	v_cmp_ne_u64_e64 s[0:1], 0, v[18:19]
	v_lshl_add_u64 v[18:19], v[148:149], 2, v[18:19]
	v_cvt_pk_bf16_f32 v22, v14, v15
	v_cvt_pk_bf16_f32 v23, v16, v17
	v_cvt_pk_bf16_f32 v24, v10, v11
	v_cvt_pk_bf16_f32 v25, v12, v13
	ds_bpermute_b32 v22, v164, v22
	ds_bpermute_b32 v23, v164, v23
	ds_bpermute_b32 v24, v164, v24
	ds_bpermute_b32 v25, v164, v25
	v_lshl_add_u64 v[168:169], v[166:167], 0, v[20:21]
	s_waitcnt lgkmcnt(4)
	global_store_dwordx4 v[170:171], v[26:29], off offset:256
	s_and_saveexec_b64 s[22:23], s[0:1]
	s_cbranch_execz .LBB0_790
	global_store_dwordx4 v[18:19], v[14:17], off
	global_store_dwordx4 v[18:19], v[10:13], off offset:16
.LBB0_790:
	s_or_b64 exec, exec, s[22:23]
	s_nop 0
	v_cvt_pk_bf16_f32 v10, v6, v7
	v_cvt_pk_bf16_f32 v11, v8, v9
	v_cvt_pk_bf16_f32 v12, v2, v3
	v_cvt_pk_bf16_f32 v13, v4, v5
	ds_bpermute_b32 v10, v164, v10
	ds_bpermute_b32 v11, v164, v11
	ds_bpermute_b32 v12, v164, v12
	ds_bpermute_b32 v13, v164, v13
	v_lshl_add_u64 v[170:171], v[166:167], 0, v[20:21]
	s_waitcnt lgkmcnt(4)
	global_store_dwordx4 v[168:169], v[22:25], off
	s_waitcnt lgkmcnt(0)
	global_store_dwordx4 v[170:171], v[10:13], off offset:256
	s_and_saveexec_b64 s[22:23], s[0:1]
	s_cbranch_execz .LBB0_729
	global_store_dwordx4 v[18:19], v[6:9], off offset:512
	global_store_dwordx4 v[18:19], v[2:5], off offset:528
	s_branch .LBB0_729
